# static s_setprio 1 for waves 0-3 (the leading half of the GEMM template) through P3-P5, no per-phase flips
# speedup vs baseline: 1.0097x; 1.0002x over previous
; __device__ __forceinline__ unsigned xb_ld(unsigned* p)              { return __hip_atomic_load(p, __ATOMIC_RELAXED, __HIP_MEMORY_SCOPE_AGENT); }
; __device__ __forceinline__ void xcd_barrier_complete(unsigned* bar, unsigned x, unsigned& nloc, unsigned& nx) {
;     const unsigned G = gridDim.x * gridDim.y * gridDim.z;
;     unsigned sum, cnt, mine, sp = 0u;
;     for (;;) {
;         sum = 0u; cnt = 0u; mine = 0u;
; #pragma unroll
;         for (unsigned j = 0; j < 16; ++j) { const unsigned c = xb_ld(&bar[XB_XCNT(j)]); sum += c; cnt += (c > 0u) ? 1u : 0u; mine = (j == x) ? c : mine; }
; __device__ __forceinline__ void xcd_barrier(const XcdBarrier& b) {
;     asm volatile("s_waitcnt vmcnt(0)" ::: "memory");
;     __syncthreads();
;     if (threadIdx.x == 0) {
;         unsigned* bar = b.bar;
;         __builtin_amdgcn_s_waitcnt(0);
;         unsigned nloc = b.st[0], nx = b.st[1];
;         if (nloc == 0u) { xcd_barrier_complete(bar, b.x, nloc, nx); b.st[0] = nloc; b.st[1] = nx; }
.LBB0_397:
	s_setprio 0
	s_lshr_b32 s0, s33, 6
	s_cmp_lt_u32 s0, 4
	s_cbranch_scc0 .Lprio_b_done
	s_setprio 1
.Lprio_b_done:
.LBB0_398:
	s_waitcnt vmcnt(0)
	s_barrier
	s_mov_b64 s[0:1], exec
	v_readlane_b32 s2, v255, 10
	v_readlane_b32 s3, v255, 11
	s_and_b64 s[2:3], s[0:1], s[2:3]
	s_mov_b64 exec, s[2:3]
	s_cbranch_execz .LBB0_450
	s_add_i32 s2, 0, 0x22000
	v_mov_b32_e32 v0, s2
	s_waitcnt vmcnt(0) expcnt(0) lgkmcnt(0)
	ds_read_b32 v2, v0
	s_add_i32 s2, 0, 0x22004
	v_mov_b32_e32 v0, s2
	ds_read_b32 v0, v0
	s_waitcnt lgkmcnt(1)
	v_cmp_ne_u32_e32 vcc, 0, v2
	s_cbranch_vccnz .LBB0_414
	s_add_u32 s2, s80, 0x19d0200
	s_addc_u32 s3, s81, 0
	s_add_u32 s4, s80, 0x19d0400
	s_addc_u32 s5, s81, 0
	s_add_u32 s6, s80, 0x19d0500
	s_addc_u32 s7, s81, 0
	s_add_u32 s8, s80, 0x19d0600
	s_addc_u32 s9, s81, 0
	s_add_u32 s10, s80, 0x19d0700
	s_addc_u32 s11, s81, 0
	s_add_u32 s12, s80, 0x19d0800
	s_addc_u32 s13, s81, 0
	s_add_u32 s14, s80, 0x19d0900
	s_addc_u32 s15, s81, 0
	s_add_u32 s16, s80, 0x19d0a00
	s_addc_u32 s17, s81, 0
	s_add_u32 s22, s80, 0x19d0b00
	s_addc_u32 s23, s81, 0
	s_add_u32 s24, s80, 0x19d0c00
	s_addc_u32 s25, s81, 0
	s_add_u32 s26, s80, 0x19d0d00
	s_addc_u32 s27, s81, 0
	s_add_u32 s28, s80, 0x19d0e00
	s_addc_u32 s29, s81, 0
	s_add_u32 s30, s80, 0x19d0f00
	s_addc_u32 s31, s81, 0
	s_add_u32 s34, s80, 0x19d1000
	s_addc_u32 s35, s81, 0
	s_add_u32 s40, s80, 0x19d1100
	s_addc_u32 s41, s81, 0
	s_add_u32 s42, s80, 0x19d1200
	s_addc_u32 s43, s81, 0
	s_mul_i32 s33, s83, s92
	s_add_u32 s44, s80, 0x19d1300
	s_mul_i32 s33, s33, s82
	s_addc_u32 s45, s81, 0
	s_mov_b32 s52, 1
	v_mov_b32_e32 v16, 0
	s_branch .LBB0_402
